# on top of the P1 slack rebalancing: next-layer W_in conversion items go to workgroups 64..103 (one first-loop item each) instead of 176..215
# baseline (speedup 1.0000x reference)
; #define LAS __attribute__((address_space(3)))
; template <int MODE  >
; __device__ __forceinline__ void p0_transpose_item(const float* W, int K, int N, const float* gain, bf16_t* WT, LAS float* scr, int item, int lane) {
;     const int nblk = N / 64, kb = item / nblk, nb = item % nblk, k0 = 64 * kb, n0 = 64 * nb;
;     const __amdgpu_buffer_rsrc_t wrs = __builtin_amdgcn_make_buffer_rsrc(WT, 0, N * K * 2, 0x00020000);
;     const int lr = lane >> 4, lc = 4 * (lane & 15);
;     f32x4 v[16];
; #pragma unroll
;     for (int i = 0; i < 16; ++i) v[i] = __builtin_nontemporal_load((const f32x4*)(W + (size_t)(k0 + 4 * i + lr) * N + n0 + lc));
; __global__ void __launch_bounds__(512, 2) mk_fwd(Args a) {
;     ...
;                 if (layer + 1 < DEPTH) for (int it = gw; it < (DM / 64) * (INW / 64); it += NGW) p0_transpose_item<0>(a.w_in + (size_t)(layer + 1) * DM * INW, DM, INW, a.norm1 + (layer + 1) * DM, WINN, scr, it, lane);
.LBB0_355:
	s_or_b64 exec, exec, s[20:21]
	v_readlane_b32 s8, v255, 41
	s_movk_i32 s5, 0x140
	v_readlane_b32 s9, v255, 42
	v_cmp_gt_u32_e32 vcc, s5, v69
	s_xor_b64 s[8:9], s[8:9], -1
	s_and_b64 s[8:9], s[8:9], vcc
	s_and_saveexec_b64 s[10:11], s[8:9]
	v_readlane_b32 s12, v255, 28
	v_readlane_b32 s14, v255, 30
	v_readlane_b32 s13, v255, 29
	v_readlane_b32 s15, v255, 31
	s_cbranch_execz .LBB0_358
	s_and_b64 s[8:9], s[64:65], exec
	s_cselect_b32 s5, 0xfc00000, s6
	s_add_u32 s12, s92, s5
	s_mul_i32 s8, s52, 0x140000
	s_mov_b32 s9, s59
	v_readlane_b32 s64, v253, 9
	s_addc_u32 s5, s93, 0
	s_lshl_b64 s[8:9], s[8:9], 2
	v_readlane_b32 s68, v253, 13
	v_readlane_b32 s69, v253, 14
	s_add_u32 s8, s68, s8
	s_addc_u32 s9, s69, s9
	s_lshl_b32 s16, s52, 10
	s_mov_b32 s17, s59
	v_readlane_b32 s66, v253, 11
	s_lshl_b64 s[16:17], s[16:17], 2
	v_lshlrev_b32_e32 v0, 11, v90
	v_and_b32_e32 v1, 7, v184
	v_readlane_b32 s67, v253, 12
	s_add_u32 s16, s66, s16
	v_mov_b32_e32 v73, v201
	v_lshl_or_b32 v0, v69, 17, v0
	v_lshlrev_b32_e32 v1, 4, v1
	s_mov_b32 s1, 0x1c000
	s_addc_u32 s17, s67, s17
	v_lshl_add_u64 v[56:57], s[8:9], 0, v[72:73]
	s_and_b32 s13, s5, 0xffff
	s_mov_b32 s15, s95
	v_or3_b32 v58, v0, v1, s1
	s_lshl_b32 s5, s37, 17
	s_lshl_b32 s7, s37, 6
	s_mov_b64 s[20:21], 0
	v_readlane_b32 s65, v253, 10
	v_readlane_b32 s70, v253, 15
	v_readlane_b32 s71, v253, 16
	v_readlane_b32 s72, v253, 17
	v_readlane_b32 s73, v253, 18
	v_readlane_b32 s74, v253, 19
	v_readlane_b32 s75, v253, 20
	v_readlane_b32 s76, v253, 21
	v_readlane_b32 s77, v253, 22
	v_readlane_b32 s78, v253, 23
	v_readlane_b32 s79, v253, 24
